# SEL softmax: tile row-sum used as overflow detector, row-max and rescale only on rare out-of-line slow path
# speedup vs baseline: 1.0128x; 1.0017x over previous
.LBB0_632:
	s_nop 9
	v_cndmask_b32_e64 v222, -v248, v203, s[6:7]
	v_fma_f32 v0, v66, s66, -v222
	v_exp_f32_e32 v204, v0
	v_fma_f32 v0, v67, s66, -v222
	v_exp_f32_e32 v205, v0
	v_fma_f32 v0, v68, s66, -v222
	v_exp_f32_e32 v206, v0
	v_fma_f32 v0, v69, s66, -v222
	v_exp_f32_e32 v207, v0
	v_fma_f32 v0, v70, s66, -v222
	v_exp_f32_e32 v208, v0
	v_fma_f32 v0, v71, s66, -v222
	v_exp_f32_e32 v209, v0
	v_fma_f32 v0, v72, s66, -v222
	v_exp_f32_e32 v210, v0
	v_fma_f32 v0, v73, s66, -v222
	v_exp_f32_e32 v211, v0
	v_fma_f32 v0, v74, s66, -v222
	v_exp_f32_e32 v212, v0
	v_fma_f32 v0, v75, s66, -v222
	v_exp_f32_e32 v213, v0
	v_fma_f32 v0, v76, s66, -v222
	v_exp_f32_e32 v214, v0
	v_fma_f32 v0, v77, s66, -v222
	v_exp_f32_e32 v215, v0
	v_fma_f32 v0, v78, s66, -v222
	v_exp_f32_e32 v216, v0
	v_fma_f32 v0, v79, s66, -v222
	v_exp_f32_e32 v217, v0
	v_fma_f32 v0, v80, s66, -v222
	v_exp_f32_e32 v218, v0
	v_fma_f32 v0, v81, s66, -v222
	v_exp_f32_e32 v219, v0
	v_add_f32_e32 v196, v204, v205
	v_add_f32_e32 v196, v206, v196
	v_add_f32_e32 v196, v207, v196
	v_add_f32_e32 v196, v208, v196
	v_add_f32_e32 v196, v209, v196
	v_add_f32_e32 v196, v210, v196
	v_add_f32_e32 v196, v211, v196
	v_add_f32_e32 v196, v212, v196
	v_add_f32_e32 v196, v213, v196
	v_add_f32_e32 v196, v214, v196
	v_add_f32_e32 v196, v215, v196
	v_add_f32_e32 v196, v216, v196
	v_add_f32_e32 v196, v217, v196
	v_add_f32_e32 v196, v218, v196
	v_add_f32_e32 v196, v219, v196
	v_cmp_lt_f32_e32 vcc, 0x43800000, v196
	s_cbranch_vccnz .Lsel_slow0
.Lsel_join0:
	v_add_f32_e32 v151, v151, v196
	v_cvt_pk_bf16_f32 v66, v204, v205
	v_cvt_pk_bf16_f32 v67, v206, v207
	v_cvt_pk_bf16_f32 v68, v208, v209
	v_cvt_pk_bf16_f32 v69, v210, v211
	v_cvt_pk_bf16_f32 v70, v212, v213
	v_cvt_pk_bf16_f32 v71, v214, v215
	v_cvt_pk_bf16_f32 v72, v216, v217
	v_cvt_pk_bf16_f32 v73, v218, v219
	s_waitcnt vmcnt(0) lgkmcnt(0)
	v_mfma_f32_32x32x16_bf16 v[50:65], v[142:145], v[66:69], v[50:65]
	s_lshl_b32 s8, s90, 5
	s_add_i32 s8, s8, s91
	s_lshl_b32 s98, s8, 7
	v_lshl_add_u64 v[220:221], v[240:241], 0, s[98:99]
	s_xor_b64 s[6:7], s[56:57], -1
	v_mfma_f32_32x32x16_bf16 v[34:49], v[134:137], v[66:69], v[34:49]
	s_andn2_b64 vcc, exec, s[6:7]
	v_mfma_f32_32x32x16_bf16 v[50:65], v[138:141], v[70:73], v[50:65]
	v_mfma_f32_32x32x16_bf16 v[34:49], v[130:133], v[70:73], v[34:49]
	v_mfma_f32_32x32x16_bf16 v[66:81], v[118:121], v[98:101], 0
	v_mfma_f32_32x32x16_bf16 v[66:81], v[122:125], v[102:105], v[66:81]
	v_mfma_f32_32x32x16_bf16 v[66:81], v[126:129], v[106:109], v[66:81]
	v_mfma_f32_32x32x16_bf16 v[66:81], v[114:117], v[110:113], v[66:81]
	global_load_dwordx4 v[118:121], v[220:221], off
	global_load_dwordx4 v[122:125], v[220:221], off offset:1024
	global_load_dwordx4 v[126:129], v[220:221], off offset:2048
	global_load_dwordx4 v[114:117], v[220:221], off offset:3072
	s_cbranch_vccnz .LBB0_637
	v_cmp_le_i32_e32 vcc, v186, v174
	s_and_b64 vcc, s[4:5], vcc
	s_nop 4
	v_cndmask_b32_e32 v66, v248, v66, vcc
	v_cmp_lt_i32_e32 vcc, v186, v174
	s_and_b64 vcc, s[4:5], vcc
	s_nop 0
	v_cndmask_b32_e32 v67, v248, v67, vcc
	v_cmp_le_i32_e32 vcc, v186, v175
	s_and_b64 vcc, s[4:5], vcc
	s_nop 0
	v_cndmask_b32_e32 v68, v248, v68, vcc
	v_cmp_le_i32_e32 vcc, v186, v184
	s_and_b64 vcc, s[4:5], vcc
	s_nop 0
	v_cndmask_b32_e32 v69, v248, v69, vcc
	v_cmp_le_i32_e32 vcc, v186, v172
	s_and_b64 vcc, s[4:5], vcc
	s_nop 0
	v_cndmask_b32_e32 v70, v248, v70, vcc
	v_cmp_lt_i32_e32 vcc, v186, v172
	s_and_b64 vcc, s[4:5], vcc
	s_nop 0
	v_cndmask_b32_e32 v71, v248, v71, vcc
	v_cmp_le_i32_e32 vcc, v202, v172
	s_and_b64 vcc, s[4:5], vcc
	s_nop 0
	v_cndmask_b32_e32 v72, v248, v72, vcc
	v_cmp_le_i32_e32 vcc, v200, v172
	s_and_b64 vcc, s[4:5], vcc
	s_nop 0
	v_cndmask_b32_e32 v73, v248, v73, vcc
	v_cmp_le_i32_e32 vcc, v192, v172
	s_and_b64 vcc, s[4:5], vcc
	s_nop 0
	v_cndmask_b32_e32 v74, v248, v74, vcc
	v_cmp_le_i32_e32 vcc, v201, v172
	s_and_b64 vcc, s[4:5], vcc
	s_nop 0
	v_cndmask_b32_e32 v75, v248, v75, vcc
	v_cmp_le_i32_e32 vcc, v193, v172
	s_and_b64 vcc, s[4:5], vcc
	s_nop 0
	v_cndmask_b32_e32 v76, v248, v76, vcc
	v_cmp_le_i32_e32 vcc, v191, v172
	s_and_b64 vcc, s[4:5], vcc
	s_nop 0
	v_cndmask_b32_e32 v77, v248, v77, vcc
	v_cmp_le_i32_e32 vcc, v190, v172
	s_and_b64 vcc, s[4:5], vcc
	s_nop 0
	v_cndmask_b32_e32 v78, v248, v78, vcc
	v_cmp_le_i32_e32 vcc, v189, v172
	s_and_b64 vcc, s[4:5], vcc
	s_nop 0
	v_cndmask_b32_e32 v79, v248, v79, vcc
	v_cmp_le_i32_e32 vcc, v188, v172
	s_and_b64 vcc, s[4:5], vcc
	s_nop 0
	v_cndmask_b32_e32 v80, v248, v80, vcc
	v_cmp_le_i32_e32 vcc, v187, v172
	s_and_b64 vcc, s[4:5], vcc
	s_nop 0
	v_cndmask_b32_e32 v81, v248, v81, vcc
.LBB0_637:
	s_nop 6
	v_cndmask_b32_e64 v223, -v248, v185, s[4:5]
	v_fma_f32 v0, v66, s66, -v223
	v_exp_f32_e32 v204, v0
	v_fma_f32 v0, v67, s66, -v223
	v_exp_f32_e32 v205, v0
	v_fma_f32 v0, v68, s66, -v223
	v_exp_f32_e32 v206, v0
	v_fma_f32 v0, v69, s66, -v223
	v_exp_f32_e32 v207, v0
	v_fma_f32 v0, v70, s66, -v223
	v_exp_f32_e32 v208, v0
	v_fma_f32 v0, v71, s66, -v223
	v_exp_f32_e32 v209, v0
	v_fma_f32 v0, v72, s66, -v223
	v_exp_f32_e32 v210, v0
	v_fma_f32 v0, v73, s66, -v223
	v_exp_f32_e32 v211, v0
	v_fma_f32 v0, v74, s66, -v223
	v_exp_f32_e32 v212, v0
	v_fma_f32 v0, v75, s66, -v223
	v_exp_f32_e32 v213, v0
	v_fma_f32 v0, v76, s66, -v223
	v_exp_f32_e32 v214, v0
	v_fma_f32 v0, v77, s66, -v223
	v_exp_f32_e32 v215, v0
	v_fma_f32 v0, v78, s66, -v223
	v_exp_f32_e32 v216, v0
	v_fma_f32 v0, v79, s66, -v223
	v_exp_f32_e32 v217, v0
	v_fma_f32 v0, v80, s66, -v223
	v_exp_f32_e32 v218, v0
	v_fma_f32 v0, v81, s66, -v223
	v_exp_f32_e32 v219, v0
	v_add_f32_e32 v186, v204, v205
	v_add_f32_e32 v186, v206, v186
	v_add_f32_e32 v186, v207, v186
	v_add_f32_e32 v186, v208, v186
	v_add_f32_e32 v186, v209, v186
	v_add_f32_e32 v186, v210, v186
	v_add_f32_e32 v186, v211, v186
	v_add_f32_e32 v186, v212, v186
	v_add_f32_e32 v186, v213, v186
	v_add_f32_e32 v186, v214, v186
	v_add_f32_e32 v186, v215, v186
	v_add_f32_e32 v186, v216, v186
	v_add_f32_e32 v186, v217, v186
	v_add_f32_e32 v186, v218, v186
	v_add_f32_e32 v186, v219, v186
	v_cmp_lt_f32_e32 vcc, 0x43800000, v186
	s_cbranch_vccnz .Lsel_slow1
.Lsel_join1:
	v_add_f32_e32 v150, v150, v186
	v_cvt_pk_bf16_f32 v66, v204, v205
	v_cvt_pk_bf16_f32 v67, v206, v207
	v_cvt_pk_bf16_f32 v68, v208, v209
	v_cvt_pk_bf16_f32 v69, v210, v211
	v_cvt_pk_bf16_f32 v70, v212, v213
	v_cvt_pk_bf16_f32 v71, v214, v215
	v_cvt_pk_bf16_f32 v72, v216, v217
	v_cvt_pk_bf16_f32 v73, v218, v219
	v_mfma_f32_32x32x16_bf16 v[18:33], v[142:145], v[66:69], v[18:33]
	v_mfma_f32_32x32x16_bf16 v[2:17], v[134:137], v[66:69], v[2:17]
	v_mfma_f32_32x32x16_bf16 v[18:33], v[138:141], v[70:73], v[18:33]
	v_mfma_f32_32x32x16_bf16 v[2:17], v[130:133], v[70:73], v[2:17]
	s_xor_b64 s[4:5], s[96:97], -1
	s_and_b64 vcc, exec, s[4:5]
	s_cbranch_vccnz .LBB0_642
	s_mov_b32 s8, s90
	s_mov_b32 s4, s83
	s_branch .LBB0_626
.Lsel_slow0:
	v_max_f32_e32 v0, v66, v67
	v_max3_f32 v0, v0, v68, v69
	v_max3_f32 v0, v0, v70, v71
	v_max3_f32 v0, v0, v72, v73
	v_max3_f32 v0, v0, v74, v75
	v_max3_f32 v0, v0, v76, v77
	v_max3_f32 v0, v0, v78, v79
	v_max3_f32 v0, v0, v80, v81
	v_cndmask_b32_e64 v0, v248, v0, s[6:7]
	v_mov_b32_e32 v196, v0
	s_nop 1
	v_permlane32_swap_b32_e32 v0, v196
	v_max_f32_e32 v0, v0, v196
	v_mul_f32_e32 v0, 0x3e38aa3b, v0
	v_max_f32_e32 v0, v203, v0
	v_sub_f32_e32 v196, v0, v203
	v_cmp_lt_f32_e32 vcc, s67, v196
	s_cbranch_vccz .Lsel_slow0_nr
	v_sub_f32_e32 v196, v203, v0
	v_exp_f32_e32 v204, v196
	s_nop 0
	v_mul_f32_e32 v151, v151, v204
	v_pk_mul_f32 v[64:65], v[64:65], v[204:205] op_sel_hi:[1,0]
	v_pk_mul_f32 v[62:63], v[62:63], v[204:205] op_sel_hi:[1,0]
	v_pk_mul_f32 v[60:61], v[60:61], v[204:205] op_sel_hi:[1,0]
	v_pk_mul_f32 v[58:59], v[58:59], v[204:205] op_sel_hi:[1,0]
	v_pk_mul_f32 v[56:57], v[56:57], v[204:205] op_sel_hi:[1,0]
	v_pk_mul_f32 v[54:55], v[54:55], v[204:205] op_sel_hi:[1,0]
	v_pk_mul_f32 v[52:53], v[52:53], v[204:205] op_sel_hi:[1,0]
	v_pk_mul_f32 v[50:51], v[50:51], v[204:205] op_sel_hi:[1,0]
	v_pk_mul_f32 v[48:49], v[48:49], v[204:205] op_sel_hi:[1,0]
	v_pk_mul_f32 v[46:47], v[46:47], v[204:205] op_sel_hi:[1,0]
	v_pk_mul_f32 v[44:45], v[44:45], v[204:205] op_sel_hi:[1,0]
	v_pk_mul_f32 v[42:43], v[42:43], v[204:205] op_sel_hi:[1,0]
	v_pk_mul_f32 v[40:41], v[40:41], v[204:205] op_sel_hi:[1,0]
	v_pk_mul_f32 v[38:39], v[38:39], v[204:205] op_sel_hi:[1,0]
	v_pk_mul_f32 v[36:37], v[36:37], v[204:205] op_sel_hi:[1,0]
	v_pk_mul_f32 v[34:35], v[34:35], v[204:205] op_sel_hi:[1,0]
	v_mov_b32_e32 v203, v0
.Lsel_slow0_nr:
	v_cndmask_b32_e64 v222, -v248, v203, s[6:7]
	v_fma_f32 v0, v66, s66, -v222
	v_exp_f32_e32 v204, v0
	v_fma_f32 v0, v67, s66, -v222
	v_exp_f32_e32 v205, v0
	v_fma_f32 v0, v68, s66, -v222
	v_exp_f32_e32 v206, v0
	v_fma_f32 v0, v69, s66, -v222
	v_exp_f32_e32 v207, v0
	v_fma_f32 v0, v70, s66, -v222
	v_exp_f32_e32 v208, v0
	v_fma_f32 v0, v71, s66, -v222
	v_exp_f32_e32 v209, v0
	v_fma_f32 v0, v72, s66, -v222
	v_exp_f32_e32 v210, v0
	v_fma_f32 v0, v73, s66, -v222
	v_exp_f32_e32 v211, v0
	v_fma_f32 v0, v74, s66, -v222
	v_exp_f32_e32 v212, v0
	v_fma_f32 v0, v75, s66, -v222
	v_exp_f32_e32 v213, v0
	v_fma_f32 v0, v76, s66, -v222
	v_exp_f32_e32 v214, v0
	v_fma_f32 v0, v77, s66, -v222
	v_exp_f32_e32 v215, v0
	v_fma_f32 v0, v78, s66, -v222
	v_exp_f32_e32 v216, v0
	v_fma_f32 v0, v79, s66, -v222
	v_exp_f32_e32 v217, v0
	v_fma_f32 v0, v80, s66, -v222
	v_exp_f32_e32 v218, v0
	v_fma_f32 v0, v81, s66, -v222
	v_exp_f32_e32 v219, v0
	v_add_f32_e32 v196, v204, v205
	v_add_f32_e32 v196, v206, v196
	v_add_f32_e32 v196, v207, v196
	v_add_f32_e32 v196, v208, v196
	v_add_f32_e32 v196, v209, v196
	v_add_f32_e32 v196, v210, v196
	v_add_f32_e32 v196, v211, v196
	v_add_f32_e32 v196, v212, v196
	v_add_f32_e32 v196, v213, v196
	v_add_f32_e32 v196, v214, v196
	v_add_f32_e32 v196, v215, v196
	v_add_f32_e32 v196, v216, v196
	v_add_f32_e32 v196, v217, v196
	v_add_f32_e32 v196, v218, v196
	v_add_f32_e32 v196, v219, v196
	s_branch .Lsel_join0
.Lsel_slow1:
	v_max_f32_e32 v187, v66, v67
	v_max3_f32 v187, v187, v68, v69
	v_max3_f32 v187, v187, v70, v71
	v_max3_f32 v187, v187, v72, v73
	v_max3_f32 v187, v187, v74, v75
	v_max3_f32 v187, v187, v76, v77
	v_max3_f32 v187, v187, v78, v79
	v_max3_f32 v187, v187, v80, v81
	v_cndmask_b32_e64 v187, v248, v187, s[4:5]
	v_mov_b32_e32 v186, v187
	s_nop 1
	v_permlane32_swap_b32_e32 v187, v186
	v_max_f32_e32 v187, v187, v186
	v_mul_f32_e32 v187, 0x3e38aa3b, v187
	v_max_f32_e32 v187, v185, v187
	v_sub_f32_e32 v186, v187, v185
	v_cmp_lt_f32_e32 vcc, s67, v186
	s_cbranch_vccz .Lsel_slow1_nr
	v_sub_f32_e32 v186, v185, v187
	v_exp_f32_e32 v204, v186
	s_nop 0
	v_mul_f32_e32 v150, v150, v204
	v_pk_mul_f32 v[32:33], v[32:33], v[204:205] op_sel_hi:[1,0]
	v_pk_mul_f32 v[30:31], v[30:31], v[204:205] op_sel_hi:[1,0]
	v_pk_mul_f32 v[28:29], v[28:29], v[204:205] op_sel_hi:[1,0]
	v_pk_mul_f32 v[26:27], v[26:27], v[204:205] op_sel_hi:[1,0]
	v_pk_mul_f32 v[24:25], v[24:25], v[204:205] op_sel_hi:[1,0]
	v_pk_mul_f32 v[22:23], v[22:23], v[204:205] op_sel_hi:[1,0]
	v_pk_mul_f32 v[20:21], v[20:21], v[204:205] op_sel_hi:[1,0]
	v_pk_mul_f32 v[18:19], v[18:19], v[204:205] op_sel_hi:[1,0]
	v_pk_mul_f32 v[16:17], v[16:17], v[204:205] op_sel_hi:[1,0]
	v_pk_mul_f32 v[14:15], v[14:15], v[204:205] op_sel_hi:[1,0]
	v_pk_mul_f32 v[12:13], v[12:13], v[204:205] op_sel_hi:[1,0]
	v_pk_mul_f32 v[10:11], v[10:11], v[204:205] op_sel_hi:[1,0]
	v_pk_mul_f32 v[8:9], v[8:9], v[204:205] op_sel_hi:[1,0]
	v_pk_mul_f32 v[6:7], v[6:7], v[204:205] op_sel_hi:[1,0]
	v_pk_mul_f32 v[4:5], v[4:5], v[204:205] op_sel_hi:[1,0]
	v_pk_mul_f32 v[2:3], v[2:3], v[204:205] op_sel_hi:[1,0]
	v_mov_b32_e32 v185, v187
.Lsel_slow1_nr:
	v_cndmask_b32_e64 v223, -v248, v185, s[4:5]
	v_fma_f32 v0, v66, s66, -v223
	v_exp_f32_e32 v204, v0
	v_fma_f32 v0, v67, s66, -v223
	v_exp_f32_e32 v205, v0
	v_fma_f32 v0, v68, s66, -v223
	v_exp_f32_e32 v206, v0
	v_fma_f32 v0, v69, s66, -v223
	v_exp_f32_e32 v207, v0
	v_fma_f32 v0, v70, s66, -v223
	v_exp_f32_e32 v208, v0
	v_fma_f32 v0, v71, s66, -v223
	v_exp_f32_e32 v209, v0
	v_fma_f32 v0, v72, s66, -v223
	v_exp_f32_e32 v210, v0
	v_fma_f32 v0, v73, s66, -v223
	v_exp_f32_e32 v211, v0
	v_fma_f32 v0, v74, s66, -v223
	v_exp_f32_e32 v212, v0
	v_fma_f32 v0, v75, s66, -v223
	v_exp_f32_e32 v213, v0
	v_fma_f32 v0, v76, s66, -v223
	v_exp_f32_e32 v214, v0
	v_fma_f32 v0, v77, s66, -v223
	v_exp_f32_e32 v215, v0
	v_fma_f32 v0, v78, s66, -v223
	v_exp_f32_e32 v216, v0
	v_fma_f32 v0, v79, s66, -v223
	v_exp_f32_e32 v217, v0
	v_fma_f32 v0, v80, s66, -v223
	v_exp_f32_e32 v218, v0
	v_fma_f32 v0, v81, s66, -v223
	v_exp_f32_e32 v219, v0
	v_add_f32_e32 v186, v204, v205
	v_add_f32_e32 v186, v206, v186
	v_add_f32_e32 v186, v207, v186
	v_add_f32_e32 v186, v208, v186
	v_add_f32_e32 v186, v209, v186
	v_add_f32_e32 v186, v210, v186
	v_add_f32_e32 v186, v211, v186
	v_add_f32_e32 v186, v212, v186
	v_add_f32_e32 v186, v213, v186
	v_add_f32_e32 v186, v214, v186
	v_add_f32_e32 v186, v215, v186
	v_add_f32_e32 v186, v216, v186
	v_add_f32_e32 v186, v217, v186
	v_add_f32_e32 v186, v218, v186
	v_add_f32_e32 v186, v219, v186
	s_branch .Lsel_join1
